# v29 + out-proj epilogue: residual cache lines of iterations 1..7 touched (distinct dead registers) at the start of the first row-statistics exchange
# baseline (speedup 1.0000x reference)
.LBB0_564:
	v_lshrrev_b32_e32 v132, 1, v142
	v_and_b32_e32 v132, 24, v132
	s_lshl_b32 s100, s12, 8
	s_lshl_b32 s101, s42, 5
	s_or_b32 s100, s100, s101
	v_or_b32_e32 v132, s100, v132
	s_lshl_b32 s101, s19, 8
	v_add_u32_e32 v133, s101, v188
	v_lshlrev_b32_e32 v133, 11, v133
	v_add_u32_e32 v132, v133, v132
	s_cmp_eq_u32 s93, 0
	s_cbranch_scc1 .Lpf_f32
	v_readlane_b32 s100, v255, 14
	v_readlane_b32 s101, v255, 15
	v_lshlrev_b32_e32 v134, 1, v132
	s_nop 4
	v_add_u32_e32 v134, 0x10000, v134
	global_load_dword v239, v134, s[100:101]
	global_load_dword v240, v134, s[100:101] offset:256
	v_add_u32_e32 v134, 0x10000, v134
	global_load_dword v241, v134, s[100:101]
	global_load_dword v242, v134, s[100:101] offset:256
	v_add_u32_e32 v134, 0x10000, v134
	global_load_dword v243, v134, s[100:101]
	global_load_dword v244, v134, s[100:101] offset:256
	v_add_u32_e32 v134, 0x50000, v134
	global_load_dword v245, v134, s[100:101]
	global_load_dword v246, v134, s[100:101] offset:256
	v_add_u32_e32 v134, 0x10000, v134
	global_load_dword v247, v134, s[100:101]
	global_load_dword v248, v134, s[100:101] offset:256
	v_add_u32_e32 v134, 0x10000, v134
	global_load_dword v249, v134, s[100:101]
	global_load_dword v250, v134, s[100:101] offset:256
	v_add_u32_e32 v134, 0x10000, v134
	global_load_dword v251, v134, s[100:101]
	global_load_dword v252, v134, s[100:101] offset:256
	s_branch .Lpf_done
.Lpf_f32:
	v_readlane_b32 s100, v254, 10
	v_readlane_b32 s101, v254, 11
	v_lshlrev_b32_e32 v134, 2, v132
	s_nop 4
	v_add_u32_e32 v134, 0x20000, v134
	global_load_dword v239, v134, s[100:101]
	global_load_dword v240, v134, s[100:101] offset:512
	v_add_u32_e32 v134, 0x20000, v134
	global_load_dword v241, v134, s[100:101]
	global_load_dword v242, v134, s[100:101] offset:512
	v_add_u32_e32 v134, 0x20000, v134
	global_load_dword v243, v134, s[100:101]
	global_load_dword v244, v134, s[100:101] offset:512
	v_add_u32_e32 v134, 0xa0000, v134
	global_load_dword v245, v134, s[100:101]
	global_load_dword v246, v134, s[100:101] offset:512
	v_add_u32_e32 v134, 0x20000, v134
	global_load_dword v247, v134, s[100:101]
	global_load_dword v248, v134, s[100:101] offset:512
	v_add_u32_e32 v134, 0x20000, v134
	global_load_dword v249, v134, s[100:101]
	global_load_dword v250, v134, s[100:101] offset:512
	v_add_u32_e32 v134, 0x20000, v134
	global_load_dword v251, v134, s[100:101]
	global_load_dword v252, v134, s[100:101] offset:512
